# P0 weight transposes: gain-scaled variants issue all 32 W + 32 gain loads together (was 1 round trip per element)
# speedup vs baseline: 1.0171x; 1.0132x over previous
; __device__ __forceinline__ void transpose_item(const float* W, int ldw, int K, int srccol0, bf16* WT, int dstrow0, const float* gain, LAS float* scr, int kb, int nb, int lane) {
;     ...
;     for (int i = 0; i < 32; ++i) { const int kk = 2 * i + (lane >> 5); float w = W[(size_t)(k0 + kk) * ldw + srccol0 + n0 + (lane & 31)]; if (gain) w *= gain[k0 + kk]; scr[kk * 33 + (lane & 31)] = w; }
; __global__ void __launch_bounds__(NWAVES * 64, 2) fwd_megakernel(Args args) {
;     ...
;             if (r < I_UP) { const int kb = r / 176, nb = r % 176, pn = nb >> 3, jb = nb & 7; const int srcc = (jb < 4) ? 128 * pn + 32 * jb : DFF + 128 * pn + 32 * (jb - 4);
;                 transpose_item(w_up, NUP, 1024, srcc - 32 * nb, Wup_t, 0, ffn_g, scr, kb, nb, lane); continue; } r -= I_UP;
.LBB0_15:
	s_andn2_b64 vcc, exec, s[4:5]
	s_cbranch_vccnz .LBB0_81
	s_add_i32 s4, s27, 0xf800
	s_and_b32 s5, s4, 0xffff
	s_mul_i32 s5, s5, 0xba2f
	s_lshr_b32 s5, s5, 23
	s_mul_i32 s6, s5, 0xb0
	s_sub_i32 s4, s4, s6
	s_and_b32 s11, s4, 0xffff
	s_and_b32 s4, s4, 7
	s_lshl_b32 s6, s11, 4
	s_and_b32 s6, s6, 0xf80
	s_lshl_b32 s10, s4, 5
	s_or_b32 s12, s6, s10
	s_add_i32 s6, s10, s6
	s_addk_i32 s6, 0xa80
	s_cmp_lt_u32 s4, 4
	s_load_dwordx8 s[36:43], s[0:1], 0x40
	s_cselect_b32 s4, s12, s6
	s_lshl_b32 s10, s11, 5
	s_sub_i32 s4, s4, s10
	s_lshl_b32 s6, s5, 6
	s_ashr_i32 s5, s4, 31
	s_lshl_b64 s[4:5], s[4:5], 2
	s_waitcnt lgkmcnt(0)
	s_add_u32 s4, s36, s4
	s_addc_u32 s5, s37, s5
	s_lshl_b32 s11, s11, 7
	s_add_u32 s4, s4, s11
	s_addc_u32 s5, s5, 0
	v_lshlrev_b32_e32 v2, 2, v182
	v_lshl_add_u64 v[16:17], s[4:5], 0, v[2:3]
	v_or_b32_e32 v186, s6, v185
	v_mad_u64_u32 v[186:187], s[12:13], v186, s22, v[16:17]
	global_load_dword v112, v[186:187], off
	v_or_b32_e32 v188, s6, v21
	v_mad_u64_u32 v[188:189], s[12:13], v188, s22, v[16:17]
	global_load_dword v113, v[188:189], off
	v_or_b32_e32 v186, s6, v23
	v_mad_u64_u32 v[186:187], s[12:13], v186, s22, v[16:17]
	global_load_dword v114, v[186:187], off
	v_or_b32_e32 v188, s6, v25
	v_mad_u64_u32 v[188:189], s[12:13], v188, s22, v[16:17]
	global_load_dword v115, v[188:189], off
	v_or_b32_e32 v186, s6, v27
	v_mad_u64_u32 v[186:187], s[12:13], v186, s22, v[16:17]
	global_load_dword v116, v[186:187], off
	v_or_b32_e32 v188, s6, v29
	v_mad_u64_u32 v[188:189], s[12:13], v188, s22, v[16:17]
	global_load_dword v117, v[188:189], off
	v_or_b32_e32 v186, s6, v31
	v_mad_u64_u32 v[186:187], s[12:13], v186, s22, v[16:17]
	global_load_dword v118, v[186:187], off
	v_or_b32_e32 v188, s6, v33
	v_mad_u64_u32 v[188:189], s[12:13], v188, s22, v[16:17]
	global_load_dword v119, v[188:189], off
	v_or_b32_e32 v186, s6, v35
	v_mad_u64_u32 v[186:187], s[12:13], v186, s22, v[16:17]
	global_load_dword v120, v[186:187], off
	v_or_b32_e32 v188, s6, v37
	v_mad_u64_u32 v[188:189], s[12:13], v188, s22, v[16:17]
	global_load_dword v121, v[188:189], off
	v_or_b32_e32 v186, s6, v39
	v_mad_u64_u32 v[186:187], s[12:13], v186, s22, v[16:17]
	global_load_dword v122, v[186:187], off
	v_or_b32_e32 v188, s6, v41
	v_mad_u64_u32 v[188:189], s[12:13], v188, s22, v[16:17]
	global_load_dword v123, v[188:189], off
	v_or_b32_e32 v186, s6, v43
	v_mad_u64_u32 v[186:187], s[12:13], v186, s22, v[16:17]
	global_load_dword v124, v[186:187], off
	v_or_b32_e32 v188, s6, v45
	v_mad_u64_u32 v[188:189], s[12:13], v188, s22, v[16:17]
	global_load_dword v125, v[188:189], off
	v_or_b32_e32 v186, s6, v47
	v_mad_u64_u32 v[186:187], s[12:13], v186, s22, v[16:17]
	global_load_dword v126, v[186:187], off
	v_or_b32_e32 v188, s6, v49
	v_mad_u64_u32 v[188:189], s[12:13], v188, s22, v[16:17]
	global_load_dword v127, v[188:189], off
	v_or_b32_e32 v186, s6, v51
	v_mad_u64_u32 v[186:187], s[12:13], v186, s22, v[16:17]
	global_load_dword v128, v[186:187], off
	v_or_b32_e32 v188, s6, v53
	v_mad_u64_u32 v[188:189], s[12:13], v188, s22, v[16:17]
	global_load_dword v129, v[188:189], off
	v_or_b32_e32 v186, s6, v55
	v_mad_u64_u32 v[186:187], s[12:13], v186, s22, v[16:17]
	global_load_dword v130, v[186:187], off
	v_or_b32_e32 v188, s6, v57
	v_mad_u64_u32 v[188:189], s[12:13], v188, s22, v[16:17]
	global_load_dword v131, v[188:189], off
	v_or_b32_e32 v186, s6, v58
	v_mad_u64_u32 v[186:187], s[12:13], v186, s22, v[16:17]
	global_load_dword v132, v[186:187], off
	v_or_b32_e32 v188, s6, v59
	v_mad_u64_u32 v[188:189], s[12:13], v188, s22, v[16:17]
	global_load_dword v133, v[188:189], off
	v_or_b32_e32 v186, s6, v60
	v_mad_u64_u32 v[186:187], s[12:13], v186, s22, v[16:17]
	global_load_dword v134, v[186:187], off
	v_or_b32_e32 v188, s6, v61
	v_mad_u64_u32 v[188:189], s[12:13], v188, s22, v[16:17]
	global_load_dword v135, v[188:189], off
	v_or_b32_e32 v186, s6, v62
	v_mad_u64_u32 v[186:187], s[12:13], v186, s22, v[16:17]
	global_load_dword v136, v[186:187], off
	v_or_b32_e32 v188, s6, v64
	v_mad_u64_u32 v[188:189], s[12:13], v188, s22, v[16:17]
	global_load_dword v137, v[188:189], off
	v_or_b32_e32 v186, s6, v65
	v_mad_u64_u32 v[186:187], s[12:13], v186, s22, v[16:17]
	global_load_dword v138, v[186:187], off
	v_or_b32_e32 v188, s6, v66
	v_mad_u64_u32 v[188:189], s[12:13], v188, s22, v[16:17]
	global_load_dword v139, v[188:189], off
	v_or_b32_e32 v186, s6, v67
	v_mad_u64_u32 v[186:187], s[12:13], v186, s22, v[16:17]
	global_load_dword v140, v[186:187], off
	v_or_b32_e32 v188, s6, v68
	v_mad_u64_u32 v[188:189], s[12:13], v188, s22, v[16:17]
	global_load_dword v141, v[188:189], off
	v_or_b32_e32 v186, s6, v69
	v_mad_u64_u32 v[186:187], s[12:13], v186, s22, v[16:17]
	global_load_dword v142, v[186:187], off
	v_or_b32_e32 v188, s6, v70
	v_mad_u64_u32 v[188:189], s[12:13], v188, s22, v[16:17]
	global_load_dword v143, v[188:189], off
	v_mov_b32_e32 v144, 1.0
	v_mov_b32_e32 v145, 1.0
	v_mov_b32_e32 v146, 1.0
	v_mov_b32_e32 v147, 1.0
	v_mov_b32_e32 v148, 1.0
	v_mov_b32_e32 v149, 1.0
	v_mov_b32_e32 v150, 1.0
	v_mov_b32_e32 v151, 1.0
	v_mov_b32_e32 v152, 1.0
	v_mov_b32_e32 v153, 1.0
	v_mov_b32_e32 v154, 1.0
	v_mov_b32_e32 v155, 1.0
	v_mov_b32_e32 v156, 1.0
	v_mov_b32_e32 v157, 1.0
	v_mov_b32_e32 v158, 1.0
	v_mov_b32_e32 v159, 1.0
	v_mov_b32_e32 v160, 1.0
	v_mov_b32_e32 v161, 1.0
	v_mov_b32_e32 v162, 1.0
	v_mov_b32_e32 v163, 1.0
	v_mov_b32_e32 v164, 1.0
	v_mov_b32_e32 v165, 1.0
	v_mov_b32_e32 v166, 1.0
	v_mov_b32_e32 v167, 1.0
	v_mov_b32_e32 v168, 1.0
	v_mov_b32_e32 v169, 1.0
	v_mov_b32_e32 v170, 1.0
	v_mov_b32_e32 v171, 1.0
	v_mov_b32_e32 v172, 1.0
	v_mov_b32_e32 v173, 1.0
	v_mov_b32_e32 v174, 1.0
	v_mov_b32_e32 v175, 1.0
	s_and_b64 vcc, exec, s[8:9]
	s_cbranch_vccz .Lxp_up_nogain
; #define LDS_WAIT() asm volatile("s_waitcnt lgkmcnt(0)" ::: "memory")
; __device__ __forceinline__ void transpose_item(const float* W, int ldw, int K, int srccol0, bf16* WT, int dstrow0, const float* gain, LAS float* scr, int kb, int nb, int lane) {
;     ...
;     for (int i = 0; i < 32; ++i) { const int kk = 2 * i + (lane >> 5); float w = W[(size_t)(k0 + kk) * ldw + srccol0 + n0 + (lane & 31)]; if (gain) w *= gain[k0 + kk]; scr[kk * 33 + (lane & 31)] = w; }
;     LDS_WAIT(); asm volatile("" ::: "memory");
	v_add_lshl_u32 v186, v185, s6, 2
	global_load_dword v144, v186, s[86:87]
	global_load_dword v145, v186, s[86:87] offset:8
	global_load_dword v146, v186, s[86:87] offset:16
	global_load_dword v147, v186, s[86:87] offset:24
	global_load_dword v148, v186, s[86:87] offset:32
	global_load_dword v149, v186, s[86:87] offset:40
	global_load_dword v150, v186, s[86:87] offset:48
	global_load_dword v151, v186, s[86:87] offset:56
	global_load_dword v152, v186, s[86:87] offset:64
	global_load_dword v153, v186, s[86:87] offset:72
	global_load_dword v154, v186, s[86:87] offset:80
	global_load_dword v155, v186, s[86:87] offset:88
	global_load_dword v156, v186, s[86:87] offset:96
	global_load_dword v157, v186, s[86:87] offset:104
	global_load_dword v158, v186, s[86:87] offset:112
	global_load_dword v159, v186, s[86:87] offset:120
	global_load_dword v160, v186, s[86:87] offset:128
	global_load_dword v161, v186, s[86:87] offset:136
	global_load_dword v162, v186, s[86:87] offset:144
	global_load_dword v163, v186, s[86:87] offset:152
	global_load_dword v164, v186, s[86:87] offset:160
	global_load_dword v165, v186, s[86:87] offset:168
	global_load_dword v166, v186, s[86:87] offset:176
	global_load_dword v167, v186, s[86:87] offset:184
	global_load_dword v168, v186, s[86:87] offset:192
	global_load_dword v169, v186, s[86:87] offset:200
	global_load_dword v170, v186, s[86:87] offset:208
	global_load_dword v171, v186, s[86:87] offset:216
	global_load_dword v172, v186, s[86:87] offset:224
	global_load_dword v173, v186, s[86:87] offset:232
	global_load_dword v174, v186, s[86:87] offset:240
	global_load_dword v175, v186, s[86:87] offset:248
.Lxp_up_nogain:
	v_add_u32_e32 v188, v1, v56
	s_waitcnt vmcnt(0)
	v_mul_f32_e32 v112, v112, v144
	v_add_u32_e32 v186, v1, v20
	ds_write_b32 v186, v112
	v_mul_f32_e32 v113, v113, v145
	v_add_u32_e32 v186, v1, v22
	ds_write_b32 v186, v113
	v_mul_f32_e32 v114, v114, v146
	v_add_u32_e32 v186, v1, v24
	ds_write_b32 v186, v114
	v_mul_f32_e32 v115, v115, v147
	v_add_u32_e32 v186, v1, v26
	ds_write_b32 v186, v115
	v_mul_f32_e32 v116, v116, v148
	v_add_u32_e32 v186, v1, v28
	ds_write_b32 v186, v116
	v_mul_f32_e32 v117, v117, v149
	v_add_u32_e32 v186, v1, v30
	ds_write_b32 v186, v117
	v_mul_f32_e32 v118, v118, v150
	v_add_u32_e32 v186, v1, v32
	ds_write_b32 v186, v118
	v_mul_f32_e32 v119, v119, v151
	v_add_u32_e32 v186, v1, v34
	ds_write_b32 v186, v119
	v_mul_f32_e32 v120, v120, v152
	v_add_u32_e32 v186, v1, v36
	ds_write_b32 v186, v120
	v_mul_f32_e32 v121, v121, v153
	v_add_u32_e32 v186, v1, v38
	ds_write_b32 v186, v121
	v_mul_f32_e32 v122, v122, v154
	v_add_u32_e32 v186, v1, v40
	ds_write_b32 v186, v122
	v_mul_f32_e32 v123, v123, v155
	v_add_u32_e32 v186, v1, v42
	ds_write_b32 v186, v123
	v_mul_f32_e32 v124, v124, v156
	v_add_u32_e32 v186, v1, v44
	ds_write_b32 v186, v124
	v_mul_f32_e32 v125, v125, v157
	v_add_u32_e32 v186, v1, v46
	ds_write_b32 v186, v125
	v_mul_f32_e32 v126, v126, v158
	v_add_u32_e32 v186, v1, v48
	ds_write_b32 v186, v126
	v_mul_f32_e32 v127, v127, v159
	v_add_u32_e32 v186, v1, v50
	ds_write_b32 v186, v127
	v_mul_f32_e32 v128, v128, v160
	v_add_u32_e32 v186, v1, v52
	ds_write_b32 v186, v128
	v_mul_f32_e32 v129, v129, v161
	v_add_u32_e32 v186, v1, v54
	ds_write_b32 v186, v129
	v_mul_f32_e32 v130, v130, v162
	ds_write_b32 v188, v130
	v_mul_f32_e32 v131, v131, v163
	ds_write_b32 v188, v131 offset:264
	v_mul_f32_e32 v132, v132, v164
	ds_write_b32 v188, v132 offset:528
	v_mul_f32_e32 v133, v133, v165
	ds_write_b32 v188, v133 offset:792
	v_mul_f32_e32 v134, v134, v166
	ds_write_b32 v188, v134 offset:1056
	v_mul_f32_e32 v135, v135, v167
	ds_write_b32 v188, v135 offset:1320
	v_mul_f32_e32 v136, v136, v168
	ds_write_b32 v188, v136 offset:1584
	v_mul_f32_e32 v137, v137, v169
	ds_write_b32 v188, v137 offset:1848
	v_mul_f32_e32 v138, v138, v170
	ds_write_b32 v188, v138 offset:2112
	v_mul_f32_e32 v139, v139, v171
	ds_write_b32 v188, v139 offset:2376
	v_mul_f32_e32 v140, v140, v172
	ds_write_b32 v188, v140 offset:2640
	v_mul_f32_e32 v141, v141, v173
	ds_write_b32 v188, v141 offset:2904
	v_mul_f32_e32 v142, v142, v174
	ds_write_b32 v188, v142 offset:3168
	v_mul_f32_e32 v143, v143, v175
	ds_write_b32 v188, v143 offset:3432
	s_waitcnt lgkmcnt(0)
	ds_read2_b32 v[74:75], v63 offset1:8
	ds_read2_b32 v[78:79], v63 offset0:33 offset1:41
	ds_read2_b32 v[80:81], v63 offset0:66 offset1:74
	ds_read2_b32 v[82:83], v63 offset0:99 offset1:107
	ds_read2_b32 v[84:85], v63 offset0:132 offset1:140
	ds_read2_b32 v[86:87], v63 offset0:165 offset1:173
	s_waitcnt lgkmcnt(5)
; #define LAS __attribute__((address_space(3)))
; __device__ __forceinline__ unsigned pk2(float lo, float hi) { return f2bf(lo) | (f2bf(hi) << 16); }
; #define LDS_WAIT() asm volatile("s_waitcnt lgkmcnt(0)" ::: "memory")
; __device__ __forceinline__ void transpose_item(const float* W, int ldw, int K, int srccol0, bf16* WT, int dstrow0, const float* gain, LAS float* scr, int kb, int nb, int lane) {
;     ...
;     const int c = lane & 7;
; #pragma unroll
;     for (int j = 0; j < 4; ++j) { const int n = (lane >> 3) + 8 * j; const LAS float* s = scr + (8 * c) * 33 + n;
;         v4u o; o.x = pk2(s[0 * 33], s[1 * 33]); o.y = pk2(s[2 * 33], s[3 * 33]); o.z = pk2(s[4 * 33], s[5 * 33]); o.w = pk2(s[6 * 33], s[7 * 33]);
;         *(v4u*)(WT + (size_t)(dstrow0 + n0 + n) * K + k0 + 8 * c) = o; }
;     LDS_WAIT(); asm volatile("" ::: "memory");
	v_bfe_u32 v2, v74, 16, 1
	v_add3_u32 v2, v74, v2, s20
	s_waitcnt lgkmcnt(4)
	v_bfe_u32 v16, v78, 16, 1
	v_lshrrev_b32_e32 v2, 16, v2
	v_add3_u32 v16, v78, v16, s20
	v_and_or_b32 v16, v16, s21, v2
	s_waitcnt lgkmcnt(3)
	v_bfe_u32 v2, v80, 16, 1
	v_add3_u32 v2, v80, v2, s20
	s_waitcnt lgkmcnt(2)
	v_bfe_u32 v17, v82, 16, 1
	ds_read2_b32 v[88:89], v63 offset0:198 offset1:206
	v_lshrrev_b32_e32 v2, 16, v2
	v_add3_u32 v17, v82, v17, s20
	ds_read2_b32 v[90:91], v63 offset0:231 offset1:239
	v_and_or_b32 v17, v17, s21, v2
	s_waitcnt lgkmcnt(3)
	v_bfe_u32 v2, v84, 16, 1
	v_add3_u32 v2, v84, v2, s20
	s_waitcnt lgkmcnt(2)
	v_bfe_u32 v18, v86, 16, 1
	v_lshrrev_b32_e32 v2, 16, v2
	v_add3_u32 v18, v86, v18, s20
	v_and_or_b32 v18, v18, s21, v2
	s_waitcnt lgkmcnt(1)
	v_bfe_u32 v2, v88, 16, 1
	v_add3_u32 v2, v88, v2, s20
	s_waitcnt lgkmcnt(0)
	v_bfe_u32 v19, v90, 16, 1
	v_lshrrev_b32_e32 v2, 16, v2
	v_add3_u32 v19, v90, v19, s20
	s_lshl_b32 s6, s6, 1
	v_and_or_b32 v19, v19, s21, v2
	v_or_b32_e32 v2, s10, v183
	v_lshl_add_u64 v[76:77], v[6:7], 0, s[6:7]
	v_lshlrev_b32_e32 v2, 11, v2
	v_lshl_add_u64 v[92:93], v[76:77], 0, v[2:3]
	v_bfe_u32 v2, v75, 16, 1
	global_store_dwordx4 v[92:93], v[16:19], off
	v_add3_u32 v2, v75, v2, s20
	v_lshrrev_b32_e32 v2, 16, v2
	v_bfe_u32 v16, v79, 16, 1
	v_add3_u32 v16, v79, v16, s20
	v_and_or_b32 v16, v16, s21, v2
	v_bfe_u32 v2, v81, 16, 1
	v_add3_u32 v2, v81, v2, s20
	v_bfe_u32 v17, v83, 16, 1
	v_lshrrev_b32_e32 v2, 16, v2
	v_add3_u32 v17, v83, v17, s20
	v_and_or_b32 v17, v17, s21, v2
	v_bfe_u32 v2, v85, 16, 1
	v_add3_u32 v2, v85, v2, s20
	v_bfe_u32 v18, v87, 16, 1
	v_lshrrev_b32_e32 v2, 16, v2
	v_add3_u32 v18, v87, v18, s20
	v_and_or_b32 v18, v18, s21, v2
	v_bfe_u32 v2, v89, 16, 1
	v_add3_u32 v2, v89, v2, s20
	v_bfe_u32 v19, v91, 16, 1
	v_lshrrev_b32_e32 v2, 16, v2
	v_add3_u32 v19, v91, v19, s20
	v_and_or_b32 v19, v19, s21, v2
	v_or_b32_e32 v2, s10, v71
	v_lshlrev_b32_e32 v2, 11, v2
	ds_read2_b32 v[74:75], v63 offset0:16 offset1:24
	v_lshl_add_u64 v[78:79], v[76:77], 0, v[2:3]
	global_store_dwordx4 v[78:79], v[16:19], off
	ds_read2_b32 v[78:79], v63 offset0:49 offset1:57
	ds_read2_b32 v[80:81], v63 offset0:82 offset1:90
	ds_read2_b32 v[82:83], v63 offset0:115 offset1:123
	s_waitcnt lgkmcnt(3)
	v_bfe_u32 v2, v74, 16, 1
	v_add3_u32 v2, v74, v2, s20
	s_waitcnt lgkmcnt(2)
	v_bfe_u32 v16, v78, 16, 1
	ds_read2_b32 v[84:85], v63 offset0:148 offset1:156
	v_lshrrev_b32_e32 v2, 16, v2
	v_add3_u32 v16, v78, v16, s20
	ds_read2_b32 v[86:87], v63 offset0:181 offset1:189
	v_and_or_b32 v16, v16, s21, v2
	s_waitcnt lgkmcnt(3)
	v_bfe_u32 v2, v80, 16, 1
	v_add3_u32 v2, v80, v2, s20
	s_waitcnt lgkmcnt(2)
	v_bfe_u32 v17, v82, 16, 1
	ds_read2_b32 v[88:89], v63 offset0:214 offset1:222
	v_lshrrev_b32_e32 v2, 16, v2
	v_add3_u32 v17, v82, v17, s20
	ds_read2_b32 v[90:91], v63 offset0:247 offset1:255
	v_and_or_b32 v17, v17, s21, v2
	s_waitcnt lgkmcnt(3)
	v_bfe_u32 v2, v84, 16, 1
	v_add3_u32 v2, v84, v2, s20
	s_waitcnt lgkmcnt(2)
	v_bfe_u32 v18, v86, 16, 1
	v_lshrrev_b32_e32 v2, 16, v2
	v_add3_u32 v18, v86, v18, s20
	v_and_or_b32 v18, v18, s21, v2
	s_waitcnt lgkmcnt(1)
	v_bfe_u32 v2, v88, 16, 1
	v_add3_u32 v2, v88, v2, s20
	s_waitcnt lgkmcnt(0)
	v_bfe_u32 v19, v90, 16, 1
	v_lshrrev_b32_e32 v2, 16, v2
	v_add3_u32 v19, v90, v19, s20
	v_and_or_b32 v19, v19, s21, v2
	v_or_b32_e32 v2, s10, v72
	v_lshlrev_b32_e32 v2, 11, v2
	v_lshl_add_u64 v[92:93], v[76:77], 0, v[2:3]
	v_bfe_u32 v2, v75, 16, 1
	global_store_dwordx4 v[92:93], v[16:19], off
	v_add3_u32 v2, v75, v2, s20
	v_lshrrev_b32_e32 v2, 16, v2
	v_bfe_u32 v16, v79, 16, 1
	v_add3_u32 v16, v79, v16, s20
	v_and_or_b32 v16, v16, s21, v2
	v_bfe_u32 v2, v81, 16, 1
	v_add3_u32 v2, v81, v2, s20
	v_bfe_u32 v17, v83, 16, 1
	v_lshrrev_b32_e32 v2, 16, v2
	v_add3_u32 v17, v83, v17, s20
	v_and_or_b32 v17, v17, s21, v2
	v_bfe_u32 v2, v85, 16, 1
	v_add3_u32 v2, v85, v2, s20
	v_bfe_u32 v18, v87, 16, 1
	v_lshrrev_b32_e32 v2, 16, v2
	v_add3_u32 v18, v87, v18, s20
	v_and_or_b32 v18, v18, s21, v2
	v_bfe_u32 v2, v89, 16, 1
	v_add3_u32 v2, v89, v2, s20
	v_bfe_u32 v19, v91, 16, 1
	v_lshrrev_b32_e32 v2, 16, v2
	v_add3_u32 v19, v91, v19, s20
	v_and_or_b32 v19, v19, s21, v2
	v_or_b32_e32 v2, s10, v73
	v_lshlrev_b32_e32 v2, 11, v2
	v_lshl_add_u64 v[74:75], v[76:77], 0, v[2:3]
	global_store_dwordx4 v[74:75], v[16:19], off
	s_waitcnt lgkmcnt(0)

; __device__ __forceinline__ void transpose_item(const float* W, int ldw, int K, int srccol0, bf16* WT, int dstrow0, const float* gain, LAS float* scr, int kb, int nb, int lane) {
;     ...
;     for (int i = 0; i < 32; ++i) { const int kk = 2 * i + (lane >> 5); float w = W[(size_t)(k0 + kk) * ldw + srccol0 + n0 + (lane & 31)]; if (gain) w *= gain[k0 + kk]; scr[kk * 33 + (lane & 31)] = w; }
; __global__ void __launch_bounds__(NWAVES * 64, 2) fwd_megakernel(Args args) {
;     ...
;             if (r < I_OUT) { const int kb = r / 32, nb = r % 32; transpose_item(w_out, 1024, 1024, 0, Wout_t, 0, (kb < 8) ? fox_g : (sb_g - 512), scr, kb, nb, lane); continue; } r -= I_OUT;
.LBB0_82:
	s_andn2_b64 vcc, exec, s[4:5]
	s_cbranch_vccnz .LBB0_148
	s_add_i32 s4, s27, 0xfffffa00
	s_cmpk_lt_u32 s4, 0x100
	s_cselect_b32 s11, s81, s15
	s_cselect_b32 s10, s80, s14
	s_add_i32 s30, s18, 0xfffff400
	s_and_b32 s29, s30, 0x7fffffc0
	s_and_b32 s28, s16, 0x3e0
	s_lshl_b32 s6, s28, 2
	v_lshl_add_u64 v[16:17], v[14:15], 0, s[6:7]
	s_movk_i32 s4, 0x1000
	v_or_b32_e32 v186, s29, v185
	v_mad_u64_u32 v[186:187], vcc, v186, s4, v[16:17]
	global_load_dword v112, v[186:187], off
	v_or_b32_e32 v188, s29, v21
	v_mad_u64_u32 v[188:189], vcc, v188, s4, v[16:17]
	global_load_dword v113, v[188:189], off
	v_or_b32_e32 v186, s29, v23
	v_mad_u64_u32 v[186:187], vcc, v186, s4, v[16:17]
	global_load_dword v114, v[186:187], off
	v_or_b32_e32 v188, s29, v25
	v_mad_u64_u32 v[188:189], vcc, v188, s4, v[16:17]
	global_load_dword v115, v[188:189], off
	v_or_b32_e32 v186, s29, v27
	v_mad_u64_u32 v[186:187], vcc, v186, s4, v[16:17]
	global_load_dword v116, v[186:187], off
	v_or_b32_e32 v188, s29, v29
	v_mad_u64_u32 v[188:189], vcc, v188, s4, v[16:17]
	global_load_dword v117, v[188:189], off
	v_or_b32_e32 v186, s29, v31
	v_mad_u64_u32 v[186:187], vcc, v186, s4, v[16:17]
	global_load_dword v118, v[186:187], off
	v_or_b32_e32 v188, s29, v33
	v_mad_u64_u32 v[188:189], vcc, v188, s4, v[16:17]
	global_load_dword v119, v[188:189], off
	v_or_b32_e32 v186, s29, v35
	v_mad_u64_u32 v[186:187], vcc, v186, s4, v[16:17]
	global_load_dword v120, v[186:187], off
	v_or_b32_e32 v188, s29, v37
	v_mad_u64_u32 v[188:189], vcc, v188, s4, v[16:17]
	global_load_dword v121, v[188:189], off
	v_or_b32_e32 v186, s29, v39
	v_mad_u64_u32 v[186:187], vcc, v186, s4, v[16:17]
	global_load_dword v122, v[186:187], off
	v_or_b32_e32 v188, s29, v41
	v_mad_u64_u32 v[188:189], vcc, v188, s4, v[16:17]
	global_load_dword v123, v[188:189], off
	v_or_b32_e32 v186, s29, v43
	v_mad_u64_u32 v[186:187], vcc, v186, s4, v[16:17]
	global_load_dword v124, v[186:187], off
	v_or_b32_e32 v188, s29, v45
	v_mad_u64_u32 v[188:189], vcc, v188, s4, v[16:17]
	global_load_dword v125, v[188:189], off
	v_or_b32_e32 v186, s29, v47
	v_mad_u64_u32 v[186:187], vcc, v186, s4, v[16:17]
	global_load_dword v126, v[186:187], off
	v_or_b32_e32 v188, s29, v49
	v_mad_u64_u32 v[188:189], vcc, v188, s4, v[16:17]
	global_load_dword v127, v[188:189], off
	v_or_b32_e32 v186, s29, v51
	v_mad_u64_u32 v[186:187], vcc, v186, s4, v[16:17]
	global_load_dword v128, v[186:187], off
	v_or_b32_e32 v188, s29, v53
	v_mad_u64_u32 v[188:189], vcc, v188, s4, v[16:17]
	global_load_dword v129, v[188:189], off
	v_or_b32_e32 v186, s29, v55
	v_mad_u64_u32 v[186:187], vcc, v186, s4, v[16:17]
	global_load_dword v130, v[186:187], off
	v_or_b32_e32 v188, s29, v57
	v_mad_u64_u32 v[188:189], vcc, v188, s4, v[16:17]
	global_load_dword v131, v[188:189], off
	v_or_b32_e32 v186, s29, v58
	v_mad_u64_u32 v[186:187], vcc, v186, s4, v[16:17]
	global_load_dword v132, v[186:187], off
	v_or_b32_e32 v188, s29, v59
	v_mad_u64_u32 v[188:189], vcc, v188, s4, v[16:17]
	global_load_dword v133, v[188:189], off
	v_or_b32_e32 v186, s29, v60
	v_mad_u64_u32 v[186:187], vcc, v186, s4, v[16:17]
	global_load_dword v134, v[186:187], off
	v_or_b32_e32 v188, s29, v61
	v_mad_u64_u32 v[188:189], vcc, v188, s4, v[16:17]
	global_load_dword v135, v[188:189], off
	v_or_b32_e32 v186, s29, v62
	v_mad_u64_u32 v[186:187], vcc, v186, s4, v[16:17]
	global_load_dword v136, v[186:187], off
	v_or_b32_e32 v188, s29, v64
	v_mad_u64_u32 v[188:189], vcc, v188, s4, v[16:17]
	global_load_dword v137, v[188:189], off
	v_or_b32_e32 v186, s29, v65
	v_mad_u64_u32 v[186:187], vcc, v186, s4, v[16:17]
	global_load_dword v138, v[186:187], off
	v_or_b32_e32 v188, s29, v66
	v_mad_u64_u32 v[188:189], vcc, v188, s4, v[16:17]
	global_load_dword v139, v[188:189], off
	v_or_b32_e32 v186, s29, v67
	v_mad_u64_u32 v[186:187], vcc, v186, s4, v[16:17]
	global_load_dword v140, v[186:187], off
	v_or_b32_e32 v188, s29, v68
	v_mad_u64_u32 v[188:189], vcc, v188, s4, v[16:17]
	global_load_dword v141, v[188:189], off
	v_or_b32_e32 v186, s29, v69
	v_mad_u64_u32 v[186:187], vcc, v186, s4, v[16:17]
	global_load_dword v142, v[186:187], off
	v_or_b32_e32 v188, s29, v70
	v_mad_u64_u32 v[188:189], vcc, v188, s4, v[16:17]
	global_load_dword v143, v[188:189], off
	v_mov_b32_e32 v144, 1.0
	v_mov_b32_e32 v145, 1.0
	v_mov_b32_e32 v146, 1.0
	v_mov_b32_e32 v147, 1.0
	v_mov_b32_e32 v148, 1.0
	v_mov_b32_e32 v149, 1.0
	v_mov_b32_e32 v150, 1.0
	v_mov_b32_e32 v151, 1.0
	v_mov_b32_e32 v152, 1.0
	v_mov_b32_e32 v153, 1.0
	v_mov_b32_e32 v154, 1.0
	v_mov_b32_e32 v155, 1.0
	v_mov_b32_e32 v156, 1.0
	v_mov_b32_e32 v157, 1.0
	v_mov_b32_e32 v158, 1.0
	v_mov_b32_e32 v159, 1.0
	v_mov_b32_e32 v160, 1.0
	v_mov_b32_e32 v161, 1.0
	v_mov_b32_e32 v162, 1.0
	v_mov_b32_e32 v163, 1.0
	v_mov_b32_e32 v164, 1.0
	v_mov_b32_e32 v165, 1.0
	v_mov_b32_e32 v166, 1.0
	v_mov_b32_e32 v167, 1.0
	v_mov_b32_e32 v168, 1.0
	v_mov_b32_e32 v169, 1.0
	v_mov_b32_e32 v170, 1.0
	v_mov_b32_e32 v171, 1.0
	v_mov_b32_e32 v172, 1.0
	v_mov_b32_e32 v173, 1.0
	v_mov_b32_e32 v174, 1.0
	v_mov_b32_e32 v175, 1.0
	s_cmp_eq_u64 s[10:11], 0
	s_cbranch_scc1 .Lxp_out_nogain
	v_add_u32_e32 v186, s29, v185
	v_mov_b32_e32 v187, 0
	v_lshl_add_u64 v[186:187], v[186:187], 2, s[10:11]
	global_load_dword v144, v[186:187], off
	global_load_dword v145, v[186:187], off offset:8
	global_load_dword v146, v[186:187], off offset:16
	global_load_dword v147, v[186:187], off offset:24
	global_load_dword v148, v[186:187], off offset:32
	global_load_dword v149, v[186:187], off offset:40
	global_load_dword v150, v[186:187], off offset:48
	global_load_dword v151, v[186:187], off offset:56
	global_load_dword v152, v[186:187], off offset:64
	global_load_dword v153, v[186:187], off offset:72
	global_load_dword v154, v[186:187], off offset:80
	global_load_dword v155, v[186:187], off offset:88
	global_load_dword v156, v[186:187], off offset:96
	global_load_dword v157, v[186:187], off offset:104
	global_load_dword v158, v[186:187], off offset:112
	global_load_dword v159, v[186:187], off offset:120
	global_load_dword v160, v[186:187], off offset:128
	global_load_dword v161, v[186:187], off offset:136
	global_load_dword v162, v[186:187], off offset:144
	global_load_dword v163, v[186:187], off offset:152
	global_load_dword v164, v[186:187], off offset:160
	global_load_dword v165, v[186:187], off offset:168
	global_load_dword v166, v[186:187], off offset:176
	global_load_dword v167, v[186:187], off offset:184
	global_load_dword v168, v[186:187], off offset:192
	global_load_dword v169, v[186:187], off offset:200
	global_load_dword v170, v[186:187], off offset:208
	global_load_dword v171, v[186:187], off offset:216
	global_load_dword v172, v[186:187], off offset:224
	global_load_dword v173, v[186:187], off offset:232
	global_load_dword v174, v[186:187], off offset:240
	global_load_dword v175, v[186:187], off offset:248
; #define LAS __attribute__((address_space(3)))
; __device__ __forceinline__ unsigned pk2(float lo, float hi) { return f2bf(lo) | (f2bf(hi) << 16); }
; #define LDS_WAIT() asm volatile("s_waitcnt lgkmcnt(0)" ::: "memory")
; __device__ __forceinline__ void transpose_item(const float* W, int ldw, int K, int srccol0, bf16* WT, int dstrow0, const float* gain, LAS float* scr, int kb, int nb, int lane) {
;     ...
;     for (int i = 0; i < 32; ++i) { const int kk = 2 * i + (lane >> 5); float w = W[(size_t)(k0 + kk) * ldw + srccol0 + n0 + (lane & 31)]; if (gain) w *= gain[k0 + kk]; scr[kk * 33 + (lane & 31)] = w; }
;     LDS_WAIT(); asm volatile("" ::: "memory");
;     const int c = lane & 7;
; #pragma unroll
;     for (int j = 0; j < 4; ++j) { const int n = (lane >> 3) + 8 * j; const LAS float* s = scr + (8 * c) * 33 + n;
;         v4u o; o.x = pk2(s[0 * 33], s[1 * 33]); o.y = pk2(s[2 * 33], s[3 * 33]); o.z = pk2(s[4 * 33], s[5 * 33]); o.w = pk2(s[6 * 33], s[7 * 33]);
.Lxp_out_nogain:
	v_add_u32_e32 v188, v1, v56
	s_waitcnt vmcnt(0)
	v_mul_f32_e32 v112, v112, v144
	v_add_u32_e32 v186, v1, v20
	ds_write_b32 v186, v112
	v_mul_f32_e32 v113, v113, v145
	v_add_u32_e32 v186, v1, v22
	ds_write_b32 v186, v113
	v_mul_f32_e32 v114, v114, v146
	v_add_u32_e32 v186, v1, v24
	ds_write_b32 v186, v114
	v_mul_f32_e32 v115, v115, v147
	v_add_u32_e32 v186, v1, v26
	ds_write_b32 v186, v115
	v_mul_f32_e32 v116, v116, v148
	v_add_u32_e32 v186, v1, v28
	ds_write_b32 v186, v116
	v_mul_f32_e32 v117, v117, v149
	v_add_u32_e32 v186, v1, v30
	ds_write_b32 v186, v117
	v_mul_f32_e32 v118, v118, v150
	v_add_u32_e32 v186, v1, v32
	ds_write_b32 v186, v118
	v_mul_f32_e32 v119, v119, v151
	v_add_u32_e32 v186, v1, v34
	ds_write_b32 v186, v119
	v_mul_f32_e32 v120, v120, v152
	v_add_u32_e32 v186, v1, v36
	ds_write_b32 v186, v120
	v_mul_f32_e32 v121, v121, v153
	v_add_u32_e32 v186, v1, v38
	ds_write_b32 v186, v121
	v_mul_f32_e32 v122, v122, v154
	v_add_u32_e32 v186, v1, v40
	ds_write_b32 v186, v122
	v_mul_f32_e32 v123, v123, v155
	v_add_u32_e32 v186, v1, v42
	ds_write_b32 v186, v123
	v_mul_f32_e32 v124, v124, v156
	v_add_u32_e32 v186, v1, v44
	ds_write_b32 v186, v124
	v_mul_f32_e32 v125, v125, v157
	v_add_u32_e32 v186, v1, v46
	ds_write_b32 v186, v125
	v_mul_f32_e32 v126, v126, v158
	v_add_u32_e32 v186, v1, v48
	ds_write_b32 v186, v126
	v_mul_f32_e32 v127, v127, v159
	v_add_u32_e32 v186, v1, v50
	ds_write_b32 v186, v127
	v_mul_f32_e32 v128, v128, v160
	v_add_u32_e32 v186, v1, v52
	ds_write_b32 v186, v128
	v_mul_f32_e32 v129, v129, v161
	v_add_u32_e32 v186, v1, v54
	ds_write_b32 v186, v129
	v_mul_f32_e32 v130, v130, v162
	ds_write_b32 v188, v130
	v_mul_f32_e32 v131, v131, v163
	ds_write_b32 v188, v131 offset:264
	v_mul_f32_e32 v132, v132, v164
	ds_write_b32 v188, v132 offset:528
	v_mul_f32_e32 v133, v133, v165
	ds_write_b32 v188, v133 offset:792
	v_mul_f32_e32 v134, v134, v166
	ds_write_b32 v188, v134 offset:1056
	v_mul_f32_e32 v135, v135, v167
	ds_write_b32 v188, v135 offset:1320
	v_mul_f32_e32 v136, v136, v168
	ds_write_b32 v188, v136 offset:1584
	v_mul_f32_e32 v137, v137, v169
	ds_write_b32 v188, v137 offset:1848
	v_mul_f32_e32 v138, v138, v170
	ds_write_b32 v188, v138 offset:2112
	v_mul_f32_e32 v139, v139, v171
	ds_write_b32 v188, v139 offset:2376
	v_mul_f32_e32 v140, v140, v172
	ds_write_b32 v188, v140 offset:2640
	v_mul_f32_e32 v141, v141, v173
	ds_write_b32 v188, v141 offset:2904
	v_mul_f32_e32 v142, v142, v174
	ds_write_b32 v188, v142 offset:3168
	v_mul_f32_e32 v143, v143, v175
	ds_write_b32 v188, v143 offset:3432
	s_waitcnt lgkmcnt(0)
	ds_read2_b32 v[74:75], v63 offset1:8
	ds_read2_b32 v[78:79], v63 offset0:33 offset1:41
	ds_read2_b32 v[80:81], v63 offset0:66 offset1:74
	ds_read2_b32 v[82:83], v63 offset0:99 offset1:107
	ds_read2_b32 v[84:85], v63 offset0:132 offset1:140
	ds_read2_b32 v[86:87], v63 offset0:165 offset1:173
	s_waitcnt lgkmcnt(5)
	v_bfe_u32 v2, v74, 16, 1
	v_add3_u32 v2, v74, v2, s20
	s_waitcnt lgkmcnt(4)
	v_bfe_u32 v16, v78, 16, 1
	v_lshrrev_b32_e32 v2, 16, v2
	v_add3_u32 v16, v78, v16, s20
	v_and_or_b32 v16, v16, s21, v2
	s_waitcnt lgkmcnt(3)
	v_bfe_u32 v2, v80, 16, 1
	v_add3_u32 v2, v80, v2, s20
	s_waitcnt lgkmcnt(2)
	v_bfe_u32 v17, v82, 16, 1
	ds_read2_b32 v[88:89], v63 offset0:198 offset1:206
	v_lshrrev_b32_e32 v2, 16, v2
	v_add3_u32 v17, v82, v17, s20
	ds_read2_b32 v[90:91], v63 offset0:231 offset1:239
	v_and_or_b32 v17, v17, s21, v2
	s_waitcnt lgkmcnt(3)
	v_bfe_u32 v2, v84, 16, 1
	v_add3_u32 v2, v84, v2, s20
	s_waitcnt lgkmcnt(2)
	v_bfe_u32 v18, v86, 16, 1
	v_lshrrev_b32_e32 v2, 16, v2
	v_add3_u32 v18, v86, v18, s20
	v_and_or_b32 v18, v18, s21, v2
	s_waitcnt lgkmcnt(1)
; #define LAS __attribute__((address_space(3)))
; __device__ __forceinline__ unsigned pk2(float lo, float hi) { return f2bf(lo) | (f2bf(hi) << 16); }
; #define LDS_WAIT() asm volatile("s_waitcnt lgkmcnt(0)" ::: "memory")
; __device__ __forceinline__ void transpose_item(const float* W, int ldw, int K, int srccol0, bf16* WT, int dstrow0, const float* gain, LAS float* scr, int kb, int nb, int lane) {
;     ...
;     const int c = lane & 7;
; #pragma unroll
;     for (int j = 0; j < 4; ++j) { const int n = (lane >> 3) + 8 * j; const LAS float* s = scr + (8 * c) * 33 + n;
;         v4u o; o.x = pk2(s[0 * 33], s[1 * 33]); o.y = pk2(s[2 * 33], s[3 * 33]); o.z = pk2(s[4 * 33], s[5 * 33]); o.w = pk2(s[6 * 33], s[7 * 33]);
;         *(v4u*)(WT + (size_t)(dstrow0 + n0 + n) * K + k0 + 8 * c) = o; }
;     LDS_WAIT(); asm volatile("" ::: "memory");
	v_bfe_u32 v2, v88, 16, 1
	v_add3_u32 v2, v88, v2, s20
	s_waitcnt lgkmcnt(0)
	v_bfe_u32 v19, v90, 16, 1
	v_lshrrev_b32_e32 v2, 16, v2
	v_add3_u32 v19, v90, v19, s20
	s_lshl_b32 s6, s29, 1
	v_and_or_b32 v19, v19, s21, v2
	v_or_b32_e32 v2, s28, v183
	v_lshl_add_u64 v[76:77], v[8:9], 0, s[6:7]
	v_lshlrev_b32_e32 v2, 11, v2
	v_lshl_add_u64 v[92:93], v[76:77], 0, v[2:3]
	v_bfe_u32 v2, v75, 16, 1
	global_store_dwordx4 v[92:93], v[16:19], off
	v_add3_u32 v2, v75, v2, s20
	v_lshrrev_b32_e32 v2, 16, v2
	v_bfe_u32 v16, v79, 16, 1
	v_add3_u32 v16, v79, v16, s20
	v_and_or_b32 v16, v16, s21, v2
	v_bfe_u32 v2, v81, 16, 1
	v_add3_u32 v2, v81, v2, s20
	v_bfe_u32 v17, v83, 16, 1
	v_lshrrev_b32_e32 v2, 16, v2
	v_add3_u32 v17, v83, v17, s20
	v_and_or_b32 v17, v17, s21, v2
	v_bfe_u32 v2, v85, 16, 1
	v_add3_u32 v2, v85, v2, s20
	v_bfe_u32 v18, v87, 16, 1
	v_lshrrev_b32_e32 v2, 16, v2
	v_add3_u32 v18, v87, v18, s20
	v_and_or_b32 v18, v18, s21, v2
	v_bfe_u32 v2, v89, 16, 1
	v_add3_u32 v2, v89, v2, s20
	v_bfe_u32 v19, v91, 16, 1
	v_lshrrev_b32_e32 v2, 16, v2
	v_add3_u32 v19, v91, v19, s20
	v_and_or_b32 v19, v19, s21, v2
	v_or_b32_e32 v2, s28, v71
	v_lshlrev_b32_e32 v2, 11, v2
	ds_read2_b32 v[74:75], v63 offset0:16 offset1:24
	v_lshl_add_u64 v[78:79], v[76:77], 0, v[2:3]
	global_store_dwordx4 v[78:79], v[16:19], off
	ds_read2_b32 v[78:79], v63 offset0:49 offset1:57
	ds_read2_b32 v[80:81], v63 offset0:82 offset1:90
	ds_read2_b32 v[82:83], v63 offset0:115 offset1:123
	s_waitcnt lgkmcnt(3)
	v_bfe_u32 v2, v74, 16, 1
	v_add3_u32 v2, v74, v2, s20
	s_waitcnt lgkmcnt(2)
	v_bfe_u32 v16, v78, 16, 1
	ds_read2_b32 v[84:85], v63 offset0:148 offset1:156
	v_lshrrev_b32_e32 v2, 16, v2
	v_add3_u32 v16, v78, v16, s20
	ds_read2_b32 v[86:87], v63 offset0:181 offset1:189
	v_and_or_b32 v16, v16, s21, v2
	s_waitcnt lgkmcnt(3)
	v_bfe_u32 v2, v80, 16, 1
	v_add3_u32 v2, v80, v2, s20
	s_waitcnt lgkmcnt(2)
	v_bfe_u32 v17, v82, 16, 1
	ds_read2_b32 v[88:89], v63 offset0:214 offset1:222
	v_lshrrev_b32_e32 v2, 16, v2
	v_add3_u32 v17, v82, v17, s20
	ds_read2_b32 v[90:91], v63 offset0:247 offset1:255
	v_and_or_b32 v17, v17, s21, v2
	s_waitcnt lgkmcnt(3)
	v_bfe_u32 v2, v84, 16, 1
	v_add3_u32 v2, v84, v2, s20
	s_waitcnt lgkmcnt(2)
	v_bfe_u32 v18, v86, 16, 1
	v_lshrrev_b32_e32 v2, 16, v2
	v_add3_u32 v18, v86, v18, s20
	v_and_or_b32 v18, v18, s21, v2
	s_waitcnt lgkmcnt(1)
	v_bfe_u32 v2, v88, 16, 1
	v_add3_u32 v2, v88, v2, s20
	s_waitcnt lgkmcnt(0)
	v_bfe_u32 v19, v90, 16, 1
	v_lshrrev_b32_e32 v2, 16, v2
	v_add3_u32 v19, v90, v19, s20
	v_and_or_b32 v19, v19, s21, v2
	v_or_b32_e32 v2, s28, v72
	v_lshlrev_b32_e32 v2, 11, v2
	v_lshl_add_u64 v[92:93], v[76:77], 0, v[2:3]
	v_bfe_u32 v2, v75, 16, 1
	global_store_dwordx4 v[92:93], v[16:19], off
	v_add3_u32 v2, v75, v2, s20
	v_lshrrev_b32_e32 v2, 16, v2
	v_bfe_u32 v16, v79, 16, 1
	v_add3_u32 v16, v79, v16, s20
	v_and_or_b32 v16, v16, s21, v2
	v_bfe_u32 v2, v81, 16, 1
	v_add3_u32 v2, v81, v2, s20
	v_bfe_u32 v17, v83, 16, 1
	v_lshrrev_b32_e32 v2, 16, v2
	v_add3_u32 v17, v83, v17, s20
	v_and_or_b32 v17, v17, s21, v2
	v_bfe_u32 v2, v85, 16, 1
	v_add3_u32 v2, v85, v2, s20
	v_bfe_u32 v18, v87, 16, 1
	v_lshrrev_b32_e32 v2, 16, v2
	v_add3_u32 v18, v87, v18, s20
	v_and_or_b32 v18, v18, s21, v2
	v_bfe_u32 v2, v89, 16, 1
	v_add3_u32 v2, v89, v2, s20
	v_bfe_u32 v19, v91, 16, 1
	v_lshrrev_b32_e32 v2, 16, v2
	v_add3_u32 v19, v91, v19, s20
	v_and_or_b32 v19, v19, s21, v2
	v_or_b32_e32 v2, s28, v73
	v_lshlrev_b32_e32 v2, 11, v2
	v_lshl_add_u64 v[74:75], v[76:77], 0, v[2:3]
	global_store_dwordx4 v[74:75], v[16:19], off
	s_waitcnt lgkmcnt(0)
